# sample attention: q/key-128 chunk loads issued with the key batch instead of after the score loop (one memory round trip less)
# baseline (speedup 1.0000x reference)
.LBB0_720:
	s_or_b64 exec, exec, s[6:7]
	s_lshl_b32 s0, s86, 1
	s_ashr_i32 s15, s86, 1
	s_and_b32 s14, s0, 2
	s_cmpk_gt_u32 s18, 0x17f
	s_barrier
	s_cbranch_scc1 .LBB0_730
	s_mul_hi_u32 s2, s79, 0x55555556
	s_mul_i32 s2, s2, 3
	s_sub_i32 s2, s79, s2
	s_lshl_b32 s0, s79, 10
	s_mul_i32 s1, s15, 12
	s_lshl_b32 s2, s2, 2
	s_add_i32 s0, s0, 0
	s_add_i32 s1, s1, s2
	s_cmpk_gt_u32 s18, 0xbf
	s_cselect_b64 s[2:3], -1, 0
	v_cndmask_b32_e64 v2, 0, 1, s[2:3]
	v_or_b32_e32 v4, s14, v2
	v_or_b32_e32 v2, s1, v4
	s_ashr_i32 s1, s1, 2
	s_mul_hi_i32 s2, s1, 0x55555556
	s_lshr_b32 s3, s2, 31
	s_add_i32 s2, s2, s3
	s_mul_i32 s2, s2, 3
	s_sub_i32 s2, s1, s2
	s_mov_b32 s1, 0x2aaaaaab
	s_lshl_b32 s4, s2, 1
	s_ashr_i32 s3, s2, 31
	v_mul_hi_i32 v2, v2, s1
	s_lshl_b32 s1, 0x80, s4
	s_lshl_b64 s[6:7], s[2:3], 3
	v_readlane_b32 s12, v246, 0
	v_readlane_b32 s13, v246, 1
	s_add_u32 s6, s12, s6
	s_addc_u32 s7, s13, s7
	s_load_dwordx4 s[8:11], s[12:13], 0xa0
	s_nop 0
	s_load_dwordx2 s[12:13], s[6:7], 0x10
	s_cmp_eq_u32 s2, 1
	s_mov_b32 s3, 0x24a0000
	s_cselect_b32 s3, s3, 0x34a0000
	s_cmp_lg_u32 s2, 0
	s_cselect_b32 s3, s3, 0x20a0000
	s_lshl_b32 s3, s3, 2
	v_lshrrev_b32_e32 v3, 31, v2
	v_ashrrev_i32_e32 v2, 1, v2
	s_waitcnt lgkmcnt(0)
	s_add_u32 s8, s8, s3
	v_add_u32_e32 v2, v2, v3
	s_addc_u32 s9, s9, 0
	s_lshl_b32 s2, s2, 2
	v_ashrrev_i32_e32 v5, 2, v2
	v_and_b32_e32 v74, 3, v2
	v_mul_hi_i32 v3, v2, 12
	v_mul_lo_u32 v2, v2, 12
	s_ashr_i32 s3, s2, 31
	v_lshl_add_u64 v[2:3], v[2:3], 0, s[2:3]
	v_or_b32_e32 v2, v2, v4
	v_or_b32_e32 v137, s1, v74
	s_add_i32 s2, s4, 7
	v_lshlrev_b32_e32 v134, 8, v4
	v_lshlrev_b32_e32 v4, s4, v178
	v_lshlrev_b32_e32 v132, s2, v5
	v_sub_u32_e32 v4, v137, v4
	v_add_u32_e32 v138, -4, v132
	v_cmp_gt_i32_e32 vcc, s1, v4
	v_mov_b32_e32 v135, 0
	v_lshlrev_b64 v[2:3], 8, v[2:3]
	v_cndmask_b32_e32 v5, v138, v132, vcc
	v_add_u32_e32 v4, v5, v4
	v_lshl_add_u64 v[18:19], s[8:9], 0, v[134:135]
	v_lshl_add_u64 v[20:21], s[12:13], 0, v[134:135]
	v_ashrrev_i32_e32 v5, 31, v4
	v_cndmask_b32_e32 v7, v19, v21, vcc
	v_cndmask_b32_e32 v6, v18, v20, vcc
	v_lshlrev_b64 v[4:5], 11, v[4:5]
	v_lshl_add_u64 v[2:3], s[10:11], 0, v[2:3]
	v_lshl_add_u64 v[30:31], v[6:7], 0, v[4:5]
	v_mov_b32_e32 v4, 0x1be00000
	v_readfirstlane_b32 s6, v2
	v_readfirstlane_b32 s7, v3
	global_load_dwordx4 v[90:93], v[30:31], off offset:16
	global_load_dwordx4 v[140:143], v[30:31], off
	s_mov_b64 s[2:3], 0x1be00000
	v_lshl_add_u64 v[126:127], v[2:3], 0, s[2:3]
	v_or_b32_e32 v14, 64, v178
	global_load_dwordx4 v[122:125], v4, s[6:7]
	global_load_dwordx4 v[10:13], v[126:127], off offset:16
	s_nop 0
	global_load_dwordx4 v[2:5], v[126:127], off offset:32
	global_load_dwordx4 v[144:147], v[30:31], off offset:32
	global_load_dwordx4 v[148:151], v[30:31], off offset:48
	global_load_dwordx4 v[6:9], v[126:127], off offset:48
	v_lshlrev_b32_e32 v32, s4, v14
	global_load_dwordx4 v[152:155], v[30:31], off offset:80
	global_load_dwordx4 v[156:159], v[30:31], off offset:64
	global_load_dwordx4 v[26:29], v[126:127], off offset:64
	global_load_dwordx4 v[14:17], v[126:127], off offset:96
	global_load_dwordx4 v[22:25], v[126:127], off offset:80
	global_load_dwordx4 v[160:163], v[30:31], off offset:112
	global_load_dwordx4 v[164:167], v[30:31], off offset:96
	v_sub_u32_e32 v32, v137, v32
	v_cmp_gt_i32_e32 vcc, s1, v32
	v_add_u32_e32 v74, v132, v74
	v_ashrrev_i32_e32 v75, 31, v74
	v_cndmask_b32_e32 v33, v138, v132, vcc
	v_add_u32_e32 v32, v33, v32
	v_ashrrev_i32_e32 v33, 31, v32
	v_cndmask_b32_e32 v19, v19, v21, vcc
	v_cndmask_b32_e32 v18, v18, v20, vcc
	v_lshlrev_b64 v[20:21], 11, v[32:33]
	v_lshl_add_u64 v[46:47], v[18:19], 0, v[20:21]
	v_lshlrev_b64 v[74:75], 11, v[74:75]
	global_load_dwordx4 v[18:21], v[126:127], off offset:112
	global_load_dwordx4 v[170:173], v[30:31], off offset:176
	global_load_dwordx4 v[174:177], v[30:31], off offset:160
	global_load_dwordx4 v[180:183], v[30:31], off offset:144
	global_load_dwordx4 v[184:187], v[30:31], off offset:128
	global_load_dwordx4 v[188:191], v[30:31], off offset:240
	global_load_dwordx4 v[192:195], v[30:31], off offset:224
	global_load_dwordx4 v[196:199], v[30:31], off offset:208
	global_load_dwordx4 v[200:203], v[30:31], off offset:192
	global_load_dwordx4 v[58:61], v[126:127], off offset:128
	global_load_dwordx4 v[38:41], v[126:127], off offset:160
	global_load_dwordx4 v[54:57], v[126:127], off offset:144
	global_load_dwordx4 v[102:105], v[46:47], off offset:48
	global_load_dwordx4 v[106:109], v[46:47], off offset:32
	global_load_dwordx4 v[118:121], v[46:47], off offset:16
	global_load_dwordx4 v[204:207], v[46:47], off
	global_load_dwordx4 v[82:85], v[46:47], off offset:112
	global_load_dwordx4 v[86:89], v[46:47], off offset:96
	global_load_dwordx4 v[94:97], v[46:47], off offset:80
	global_load_dwordx4 v[98:101], v[46:47], off offset:64
	global_load_dwordx4 v[50:53], v[46:47], off offset:176
	global_load_dwordx4 v[62:65], v[46:47], off offset:160
	global_load_dwordx4 v[70:73], v[46:47], off offset:144
	global_load_dwordx4 v[78:81], v[46:47], off offset:128
	global_load_dwordx4 v[66:69], v[126:127], off offset:176
	global_load_dwordx4 v[30:33], v[46:47], off offset:240
	global_load_dwordx4 v[34:37], v[46:47], off offset:224
	global_load_dwordx4 v[42:45], v[46:47], off offset:208
	s_nop 0
	global_load_dwordx4 v[46:49], v[46:47], off offset:192
	v_lshl_add_u64 v[74:75], s[12:13], 0, v[74:75]
	v_lshl_add_u64 v[128:129], v[74:75], 0, v[134:135]
	global_load_dwordx4 v[114:117], v[126:127], off offset:192
	global_load_dwordx4 v[74:77], v[126:127], off offset:224
	global_load_dwordx4 v[110:113], v[126:127], off offset:208
	v_readfirstlane_b32 s6, v128
	v_readfirstlane_b32 s7, v129
	v_and_b32_e32 v169, 15, v0
	v_lshlrev_b32_e32 v130, 4, v169
	v_readfirstlane_b32 s2, v126
	v_readfirstlane_b32 s3, v127
	s_nop 4
	global_load_dwordx4 v[248:251], v130, s[6:7]
	global_load_dwordx4 v[252:255], v130, s[2:3]
	s_waitcnt vmcnt(43)
	v_pk_mul_f32 v[208:209], v[90:91], v[10:11]
	v_pk_mul_f32 v[128:129], v[142:143], v[124:125]
	v_pk_mul_f32 v[140:141], v[140:141], v[122:123]
	v_add_f32_e32 v91, v128, v129
	v_add_f32_e32 v90, v140, v141
	v_pk_mul_f32 v[142:143], v[92:93], v[12:13]
	v_add_f32_e32 v128, v90, v91
	global_load_dwordx4 v[90:93], v[126:127], off offset:240
	v_add_f32_e32 v131, 0, v128
	v_add_f32_e32 v128, v208, v209
	v_add_f32_e32 v129, v142, v143
	v_add_f32_e32 v128, v128, v129
	v_add_f32_e32 v139, 0, v128
	s_waitcnt vmcnt(42)
	v_pk_mul_f32 v[128:129], v[146:147], v[4:5]
	v_pk_mul_f32 v[140:141], v[144:145], v[2:3]
	v_add_f32_e32 v128, v128, v129
	v_add_f32_e32 v140, v140, v141
	s_waitcnt vmcnt(40)
	v_pk_mul_f32 v[142:143], v[150:151], v[8:9]
	v_pk_mul_f32 v[144:145], v[148:149], v[6:7]
	v_add_f32_e32 v128, v140, v128
	v_add_f32_e32 v131, v131, v128
	v_add_f32_e32 v128, v144, v145
	v_add_f32_e32 v129, v142, v143
	v_add_f32_e32 v128, v128, v129
	v_add_f32_e32 v139, v139, v128
	s_waitcnt vmcnt(37)
	v_pk_mul_f32 v[128:129], v[158:159], v[28:29]
	v_pk_mul_f32 v[140:141], v[156:157], v[26:27]
	v_add_f32_e32 v128, v128, v129
	v_add_f32_e32 v140, v140, v141
	s_waitcnt vmcnt(35)
	v_pk_mul_f32 v[142:143], v[154:155], v[24:25]
	v_pk_mul_f32 v[144:145], v[152:153], v[22:23]
	v_add_f32_e32 v128, v140, v128
	v_add_f32_e32 v131, v131, v128
	v_add_f32_e32 v128, v144, v145
	v_add_f32_e32 v129, v142, v143
	v_add_f32_e32 v128, v128, v129
	v_add_f32_e32 v139, v139, v128
	s_waitcnt vmcnt(33)
	v_pk_mul_f32 v[128:129], v[166:167], v[16:17]
	v_pk_mul_f32 v[140:141], v[164:165], v[14:15]
	v_add_f32_e32 v128, v128, v129
	v_add_f32_e32 v140, v140, v141
	s_waitcnt vmcnt(32)
	v_pk_mul_f32 v[142:143], v[162:163], v[20:21]
	v_pk_mul_f32 v[144:145], v[160:161], v[18:19]
	v_add_f32_e32 v128, v140, v128
	v_add_f32_e32 v131, v131, v128
	v_add_f32_e32 v128, v144, v145
	v_add_f32_e32 v129, v142, v143
	v_add_f32_e32 v128, v128, v129
	v_add_f32_e32 v139, v139, v128
	s_waitcnt vmcnt(23)
	v_pk_mul_f32 v[128:129], v[186:187], v[60:61]
	v_pk_mul_f32 v[140:141], v[184:185], v[58:59]
	v_add_f32_e32 v128, v128, v129
	v_add_f32_e32 v140, v140, v141
	s_waitcnt vmcnt(21)
	v_pk_mul_f32 v[142:143], v[182:183], v[56:57]
	v_pk_mul_f32 v[144:145], v[180:181], v[54:55]
	v_add_f32_e32 v128, v140, v128
	v_add_f32_e32 v131, v131, v128
	v_add_f32_e32 v128, v144, v145
	v_add_f32_e32 v129, v142, v143
	v_add_f32_e32 v128, v128, v129
	v_add_f32_e32 v139, v139, v128
	v_pk_mul_f32 v[128:129], v[176:177], v[40:41]
	v_pk_mul_f32 v[140:141], v[174:175], v[38:39]
	v_add_f32_e32 v128, v128, v129
	v_add_f32_e32 v140, v140, v141
	s_waitcnt vmcnt(8)
	v_pk_mul_f32 v[142:143], v[172:173], v[68:69]
	v_pk_mul_f32 v[144:145], v[170:171], v[66:67]
	v_add_f32_e32 v128, v140, v128
	v_add_f32_e32 v131, v131, v128
	v_add_f32_e32 v128, v144, v145
	v_add_f32_e32 v129, v142, v143
	v_add_f32_e32 v128, v128, v129
	v_add_f32_e32 v139, v139, v128
	s_waitcnt vmcnt(3)
	v_pk_mul_f32 v[128:129], v[202:203], v[116:117]
	v_pk_mul_f32 v[140:141], v[200:201], v[114:115]
	v_add_f32_e32 v128, v128, v129
	v_add_f32_e32 v140, v140, v141
	s_waitcnt vmcnt(1)
	v_pk_mul_f32 v[142:143], v[198:199], v[112:113]
	v_pk_mul_f32 v[144:145], v[196:197], v[110:111]
	v_add_f32_e32 v128, v140, v128
	v_add_f32_e32 v131, v131, v128
	v_add_f32_e32 v128, v144, v145
	v_add_f32_e32 v129, v142, v143
	v_add_f32_e32 v128, v128, v129
	v_add_f32_e32 v139, v139, v128
	v_pk_mul_f32 v[128:129], v[194:195], v[76:77]
	v_pk_mul_f32 v[140:141], v[192:193], v[74:75]
	v_add_f32_e32 v128, v128, v129
	v_add_f32_e32 v140, v140, v141
	s_waitcnt vmcnt(0)
	v_pk_mul_f32 v[142:143], v[190:191], v[92:93]
	v_pk_mul_f32 v[144:145], v[188:189], v[90:91]
	v_add_f32_e32 v128, v140, v128
	v_add_f32_e32 v128, v131, v128
	v_add_f32_e32 v129, v144, v145
	v_add_f32_e32 v131, v142, v143
	v_add_f32_e32 v129, v129, v131
	v_add_f32_e32 v129, v139, v129
	v_add_f32_e32 v131, v128, v129
	v_pk_mul_f32 v[140:141], v[206:207], v[124:125]
	v_pk_mul_f32 v[142:143], v[204:205], v[122:123]
	v_mov_b64_e32 v[122:123], v[248:249]
	v_mov_b64_e32 v[124:125], v[250:251]
	v_mov_b64_e32 v[126:127], v[252:253]
	v_mov_b64_e32 v[128:129], v[254:255]
	v_pk_mul_f32 v[10:11], v[118:119], v[10:11]
	v_add_f32_e32 v118, v142, v143
	v_add_f32_e32 v119, v140, v141
	v_pk_mul_f32 v[4:5], v[108:109], v[4:5]
	v_pk_mul_f32 v[2:3], v[106:107], v[2:3]
	v_pk_mul_f32 v[12:13], v[120:121], v[12:13]
	v_add_f32_e32 v118, v118, v119
	v_add_f32_e32 v2, v2, v3
	v_add_f32_e32 v3, v4, v5
	v_add_f32_e32 v118, 0, v118
	v_add_f32_e32 v10, v10, v11
	v_add_f32_e32 v11, v12, v13
	v_pk_mul_f32 v[8:9], v[104:105], v[8:9]
	v_pk_mul_f32 v[6:7], v[102:103], v[6:7]
	v_add_f32_e32 v2, v2, v3
	v_add_f32_e32 v10, v10, v11
	v_add_f32_e32 v11, v118, v2
	v_add_f32_e32 v2, v6, v7
	v_add_f32_e32 v3, v8, v9
	v_add_f32_e32 v10, 0, v10
	v_add_f32_e32 v2, v2, v3
	v_add_f32_e32 v10, v10, v2
	v_pk_mul_f32 v[2:3], v[100:101], v[28:29]
	v_pk_mul_f32 v[4:5], v[98:99], v[26:27]
	v_add_f32_e32 v2, v2, v3
	v_add_f32_e32 v4, v4, v5
	v_pk_mul_f32 v[6:7], v[96:97], v[24:25]
	v_pk_mul_f32 v[8:9], v[94:95], v[22:23]
	v_add_f32_e32 v2, v4, v2
	v_add_f32_e32 v11, v11, v2
	v_add_f32_e32 v2, v8, v9
	v_add_f32_e32 v3, v6, v7
	v_add_f32_e32 v2, v2, v3
	v_add_f32_e32 v10, v10, v2
	v_pk_mul_f32 v[2:3], v[88:89], v[16:17]
	v_pk_mul_f32 v[4:5], v[86:87], v[14:15]
	v_add_f32_e32 v2, v2, v3
	v_add_f32_e32 v4, v4, v5
	v_pk_mul_f32 v[6:7], v[84:85], v[20:21]
	v_pk_mul_f32 v[8:9], v[82:83], v[18:19]
	v_add_f32_e32 v2, v4, v2
	v_add_f32_e32 v11, v11, v2
	v_add_f32_e32 v2, v8, v9
	v_add_f32_e32 v3, v6, v7
	v_add_f32_e32 v2, v2, v3
	v_add_f32_e32 v10, v10, v2
	v_pk_mul_f32 v[2:3], v[80:81], v[60:61]
	v_pk_mul_f32 v[4:5], v[78:79], v[58:59]
	v_add_f32_e32 v2, v2, v3
	v_add_f32_e32 v4, v4, v5
	v_pk_mul_f32 v[6:7], v[72:73], v[56:57]
	v_pk_mul_f32 v[8:9], v[70:71], v[54:55]
	v_add_f32_e32 v2, v4, v2
	v_add_f32_e32 v11, v11, v2
	v_add_f32_e32 v2, v8, v9
	v_add_f32_e32 v3, v6, v7
	v_add_f32_e32 v2, v2, v3
	v_add_f32_e32 v10, v10, v2
	v_pk_mul_f32 v[2:3], v[64:65], v[40:41]
	v_pk_mul_f32 v[4:5], v[62:63], v[38:39]
	v_add_f32_e32 v2, v2, v3
	v_add_f32_e32 v4, v4, v5
	v_pk_mul_f32 v[6:7], v[52:53], v[68:69]
	v_pk_mul_f32 v[8:9], v[50:51], v[66:67]
	v_add_f32_e32 v2, v4, v2
	v_add_f32_e32 v11, v11, v2
	v_add_f32_e32 v2, v8, v9
	v_add_f32_e32 v3, v6, v7
	v_add_f32_e32 v2, v2, v3
	v_add_f32_e32 v10, v10, v2
	v_pk_mul_f32 v[2:3], v[48:49], v[116:117]
	v_pk_mul_f32 v[4:5], v[46:47], v[114:115]
	v_add_f32_e32 v2, v2, v3
	v_add_f32_e32 v4, v4, v5
	v_add_f32_e32 v2, v4, v2
	v_add_f32_e32 v11, v11, v2
	v_pk_mul_f32 v[6:7], v[44:45], v[112:113]
	v_pk_mul_f32 v[8:9], v[42:43], v[110:111]
	v_cmp_eq_u32_e64 s[6:7], 0, v178
	s_waitcnt vmcnt(0)
	v_pk_mul_f32 v[2:3], v[124:125], v[128:129]
	v_pk_mul_f32 v[4:5], v[122:123], v[126:127]
	v_add_f32_e32 v2, v2, v3
	v_add_f32_e32 v4, v4, v5
	v_add_f32_e32 v4, v4, v2
	v_xor_b32_e32 v2, 1, v136
	v_cmp_lt_i32_e32 vcc, v2, v133
	v_add_f32_e32 v8, v8, v9
	s_nop 0
	v_cndmask_b32_e32 v2, v136, v2, vcc
	v_lshlrev_b32_e32 v139, 2, v2
	ds_bpermute_b32 v5, v139, v4
	v_add_f32_e32 v2, v6, v7
	v_add_f32_e32 v2, v8, v2
	v_add_f32_e32 v10, v10, v2
	v_pk_mul_f32 v[2:3], v[36:37], v[76:77]
	s_waitcnt lgkmcnt(0)
	v_add_f32_e32 v12, v4, v5
	v_xor_b32_e32 v4, 2, v136
	v_cmp_lt_i32_e32 vcc, v4, v133
	v_add_f32_e32 v2, v2, v3
	v_pk_mul_f32 v[6:7], v[32:33], v[92:93]
	v_cndmask_b32_e32 v4, v136, v4, vcc
	v_lshlrev_b32_e32 v140, 2, v4
	ds_bpermute_b32 v13, v140, v12
	v_pk_mul_f32 v[4:5], v[34:35], v[74:75]
	v_pk_mul_f32 v[8:9], v[30:31], v[90:91]
	v_add_f32_e32 v4, v4, v5
	v_add_f32_e32 v2, v4, v2
	s_waitcnt lgkmcnt(0)
	v_add_f32_e32 v5, v12, v13
	v_xor_b32_e32 v12, 4, v136
	v_cmp_lt_i32_e32 vcc, v12, v133
	v_add_f32_e32 v3, v8, v9
	v_add_f32_e32 v6, v6, v7
	v_cndmask_b32_e32 v12, v136, v12, vcc
	v_lshlrev_b32_e32 v141, 2, v12
	ds_bpermute_b32 v12, v141, v5
	v_add_f32_e32 v3, v3, v6
	v_add_f32_e32 v2, v11, v2
	v_add_f32_e32 v3, v10, v3
	v_add_f32_e32 v2, v2, v3
	s_waitcnt lgkmcnt(0)
	v_add_f32_e32 v4, v5, v12
	v_xor_b32_e32 v5, 8, v136
	v_cmp_lt_i32_e32 vcc, v5, v133
	s_nop 1
	v_cndmask_b32_e32 v5, v136, v5, vcc
	v_lshlrev_b32_e32 v142, 2, v5
	ds_bpermute_b32 v5, v142, v4
	s_waitcnt lgkmcnt(0)
	v_add_f32_e32 v3, v4, v5
	v_max3_f32 v4, v131, v2, v3
	ds_bpermute_b32 v5, v139, v4
	s_waitcnt lgkmcnt(0)
	v_max_f32_e32 v5, v5, v5
	v_max_f32_e32 v4, v4, v5
	ds_bpermute_b32 v5, v140, v4
	s_waitcnt lgkmcnt(0)
	v_max_f32_e32 v5, v5, v5
	v_max_f32_e32 v4, v4, v5
	ds_bpermute_b32 v5, v141, v4
	s_waitcnt lgkmcnt(0)
	v_max_f32_e32 v5, v5, v5
	v_max_f32_e32 v4, v4, v5
	ds_bpermute_b32 v5, v142, v4
	s_waitcnt lgkmcnt(0)
	v_max_f32_e32 v5, v5, v5
	v_max_f32_e32 v4, v4, v5
	v_xor_b32_e32 v5, 16, v136
	v_cmp_lt_i32_e32 vcc, v5, v133
	s_nop 1
	v_cndmask_b32_e32 v5, v136, v5, vcc
	v_lshlrev_b32_e32 v171, 2, v5
	ds_bpermute_b32 v5, v171, v4
	s_waitcnt lgkmcnt(0)
	v_max_f32_e32 v5, v5, v5
	v_max_f32_e32 v4, v4, v5
	ds_bpermute_b32 v5, v168, v4
	s_waitcnt lgkmcnt(0)
	v_max_f32_e32 v5, v5, v5
	v_max_f32_e32 v170, v4, v5
	v_sub_f32_e32 v2, v2, v170
	v_sub_f32_e32 v4, v131, v170
	v_exp_f32_e32 v143, v2
	v_sub_f32_e32 v2, v3, v170
	v_exp_f32_e32 v136, v4
	v_exp_f32_e32 v172, v2
	v_lshl_add_u32 v2, v178, 2, s0
	ds_write2st64_b32 v2, v136, v143 offset0:32 offset1:33
	s_and_saveexec_b64 s[2:3], s[6:7]
	v_mov_b32_e32 v2, s0
	ds_write_b32 v2, v172 offset:8704
	s_or_b64 exec, exec, s[2:3]
	v_lshrrev_b32_e32 v144, 4, v178
	v_lshlrev_b32_e32 v2, s4, v144
	v_or_b32_e32 v6, 4, v144
	v_sub_u32_e32 v2, v137, v2
	v_lshlrev_b32_e32 v6, s4, v6
	v_or_b32_e32 v10, 8, v144
	v_cmp_gt_i32_e32 vcc, s1, v2
	v_mov_b32_e32 v126, s9
	v_mov_b32_e32 v127, s13
	v_mov_b32_e32 v128, s8
	v_mov_b32_e32 v129, s12
	v_sub_u32_e32 v6, v137, v6
	v_lshlrev_b32_e32 v10, s4, v10
	v_or_b32_e32 v14, 12, v144
	v_cndmask_b32_e32 v3, v138, v132, vcc
	v_cndmask_b32_e32 v5, v126, v127, vcc
	v_cndmask_b32_e32 v4, v128, v129, vcc
	v_cmp_gt_i32_e32 vcc, s1, v6
	v_sub_u32_e32 v10, v137, v10
	v_lshlrev_b32_e32 v14, s4, v14
	v_or_b32_e32 v18, 16, v144
	v_cndmask_b32_e32 v7, v138, v132, vcc
	v_cndmask_b32_e32 v9, v126, v127, vcc
	v_cndmask_b32_e32 v8, v128, v129, vcc
	v_cmp_gt_i32_e32 vcc, s1, v10
	v_sub_u32_e32 v14, v137, v14
	v_lshlrev_b32_e32 v18, s4, v18
	v_or_b32_e32 v22, 20, v144
	v_cndmask_b32_e32 v11, v138, v132, vcc
	v_cndmask_b32_e32 v13, v126, v127, vcc
	v_cndmask_b32_e32 v12, v128, v129, vcc
	v_cmp_gt_i32_e32 vcc, s1, v14
	v_sub_u32_e32 v18, v137, v18
	v_lshlrev_b32_e32 v22, s4, v22
	v_or_b32_e32 v26, 24, v144
	v_cndmask_b32_e32 v15, v138, v132, vcc
	v_cndmask_b32_e32 v17, v126, v127, vcc
	v_cndmask_b32_e32 v16, v128, v129, vcc
	v_cmp_gt_i32_e32 vcc, s1, v18
	v_sub_u32_e32 v22, v137, v22
	v_lshlrev_b32_e32 v26, s4, v26
	v_or_b32_e32 v30, 28, v144
	v_cndmask_b32_e32 v19, v138, v132, vcc
	v_cndmask_b32_e32 v21, v126, v127, vcc
	v_cndmask_b32_e32 v20, v128, v129, vcc
	v_cmp_gt_i32_e32 vcc, s1, v22
	v_sub_u32_e32 v26, v137, v26
	v_lshlrev_b32_e32 v30, s4, v30
	v_or_b32_e32 v34, 32, v144
	v_cndmask_b32_e32 v23, v138, v132, vcc
	v_cndmask_b32_e32 v25, v126, v127, vcc
	v_cndmask_b32_e32 v24, v128, v129, vcc
	v_cmp_gt_i32_e32 vcc, s1, v26
	v_sub_u32_e32 v30, v137, v30
	v_lshlrev_b32_e32 v34, s4, v34
	v_or_b32_e32 v38, 36, v144
	v_cndmask_b32_e32 v27, v138, v132, vcc
	v_cndmask_b32_e32 v29, v126, v127, vcc
	v_cndmask_b32_e32 v28, v128, v129, vcc
	v_cmp_gt_i32_e32 vcc, s1, v30
	v_sub_u32_e32 v34, v137, v34
	v_lshlrev_b32_e32 v38, s4, v38
	v_or_b32_e32 v42, 40, v144
	v_cndmask_b32_e32 v31, v138, v132, vcc
	v_cndmask_b32_e32 v33, v126, v127, vcc
	v_cndmask_b32_e32 v32, v128, v129, vcc
	v_cmp_gt_i32_e32 vcc, s1, v34
	v_sub_u32_e32 v38, v137, v38
	v_lshlrev_b32_e32 v42, s4, v42
	v_or_b32_e32 v46, 44, v144
	v_cndmask_b32_e32 v35, v138, v132, vcc
	v_cndmask_b32_e32 v37, v126, v127, vcc
	v_cndmask_b32_e32 v36, v128, v129, vcc
	v_cmp_gt_i32_e32 vcc, s1, v38
	v_sub_u32_e32 v42, v137, v42
	v_lshlrev_b32_e32 v46, s4, v46
	v_or_b32_e32 v50, 48, v144
	v_cndmask_b32_e32 v39, v138, v132, vcc
	v_cndmask_b32_e32 v41, v126, v127, vcc
	v_cndmask_b32_e32 v40, v128, v129, vcc
	v_cmp_gt_i32_e32 vcc, s1, v42
	v_sub_u32_e32 v46, v137, v46
	v_lshlrev_b32_e32 v50, s4, v50
	v_or_b32_e32 v54, 52, v144
	v_cndmask_b32_e32 v43, v138, v132, vcc
	v_cndmask_b32_e32 v45, v126, v127, vcc
	v_cndmask_b32_e32 v44, v128, v129, vcc
	v_cmp_gt_i32_e32 vcc, s1, v46
	v_sub_u32_e32 v50, v137, v50
	v_lshlrev_b32_e32 v54, s4, v54
	v_or_b32_e32 v58, 56, v144
	v_cndmask_b32_e32 v47, v138, v132, vcc
	v_cndmask_b32_e32 v49, v126, v127, vcc
	v_cndmask_b32_e32 v48, v128, v129, vcc
	v_cmp_gt_i32_e32 vcc, s1, v50
	v_sub_u32_e32 v54, v137, v54
	v_lshlrev_b32_e32 v58, s4, v58
	v_or_b32_e32 v62, 60, v144
	v_cndmask_b32_e32 v51, v138, v132, vcc
	v_cndmask_b32_e32 v53, v126, v127, vcc
	v_cndmask_b32_e32 v52, v128, v129, vcc
	v_cmp_gt_i32_e32 vcc, s1, v54
	v_sub_u32_e32 v58, v137, v58
	v_lshlrev_b32_e32 v62, s4, v62
	v_or_b32_e32 v66, 64, v144
	v_cndmask_b32_e32 v55, v138, v132, vcc
	v_cndmask_b32_e32 v57, v126, v127, vcc
	v_cndmask_b32_e32 v56, v128, v129, vcc
	v_cmp_gt_i32_e32 vcc, s1, v58
	v_sub_u32_e32 v62, v137, v62
	v_lshlrev_b32_e32 v66, s4, v66
	v_or_b32_e32 v70, 0x44, v144
	v_cndmask_b32_e32 v59, v138, v132, vcc
	v_cndmask_b32_e32 v61, v126, v127, vcc
	v_cndmask_b32_e32 v60, v128, v129, vcc
	v_cmp_gt_i32_e32 vcc, s1, v62
	v_sub_u32_e32 v66, v137, v66
	v_lshlrev_b32_e32 v70, s4, v70
	v_or_b32_e32 v74, 0x48, v144
	v_cndmask_b32_e32 v63, v138, v132, vcc
	v_cndmask_b32_e32 v65, v126, v127, vcc
	v_cndmask_b32_e32 v64, v128, v129, vcc
	v_cmp_gt_i32_e32 vcc, s1, v66
	v_sub_u32_e32 v70, v137, v70
	v_lshlrev_b32_e32 v74, s4, v74
	v_or_b32_e32 v78, 0x4c, v144
	v_cndmask_b32_e32 v67, v138, v132, vcc
	v_cndmask_b32_e32 v69, v126, v127, vcc
	v_cndmask_b32_e32 v68, v128, v129, vcc
	v_cmp_gt_i32_e32 vcc, s1, v70
	v_sub_u32_e32 v74, v137, v74
	v_lshlrev_b32_e32 v78, s4, v78
	v_or_b32_e32 v82, 0x50, v144
	v_cndmask_b32_e32 v71, v138, v132, vcc
	v_cndmask_b32_e32 v73, v126, v127, vcc
	v_cndmask_b32_e32 v72, v128, v129, vcc
	v_cmp_gt_i32_e32 vcc, s1, v74
	v_sub_u32_e32 v78, v137, v78
	v_lshlrev_b32_e32 v82, s4, v82
	v_or_b32_e32 v86, 0x54, v144
	v_cndmask_b32_e32 v75, v138, v132, vcc
	v_cndmask_b32_e32 v77, v126, v127, vcc
	v_cndmask_b32_e32 v76, v128, v129, vcc
	v_cmp_gt_i32_e32 vcc, s1, v78
	v_sub_u32_e32 v82, v137, v82
	v_lshlrev_b32_e32 v86, s4, v86
	v_or_b32_e32 v90, 0x58, v144
	v_cndmask_b32_e32 v79, v138, v132, vcc
	v_cndmask_b32_e32 v81, v126, v127, vcc
	v_cndmask_b32_e32 v80, v128, v129, vcc
	v_cmp_gt_i32_e32 vcc, s1, v82
	v_sub_u32_e32 v86, v137, v86
	v_lshlrev_b32_e32 v90, s4, v90
	v_or_b32_e32 v94, 0x5c, v144
	v_cndmask_b32_e32 v83, v138, v132, vcc
	v_cndmask_b32_e32 v85, v126, v127, vcc
	v_cndmask_b32_e32 v84, v128, v129, vcc
	v_cmp_gt_i32_e32 vcc, s1, v86
	v_sub_u32_e32 v90, v137, v90
	v_lshlrev_b32_e32 v94, s4, v94
	v_or_b32_e32 v98, 0x60, v144
	v_cndmask_b32_e32 v87, v138, v132, vcc
	v_cndmask_b32_e32 v89, v126, v127, vcc
	v_cndmask_b32_e32 v88, v128, v129, vcc
	v_cmp_gt_i32_e32 vcc, s1, v90
	v_sub_u32_e32 v94, v137, v94
	v_lshlrev_b32_e32 v98, s4, v98
	v_or_b32_e32 v102, 0x64, v144
	v_cndmask_b32_e32 v91, v138, v132, vcc
	v_cndmask_b32_e32 v93, v126, v127, vcc
	v_cndmask_b32_e32 v92, v128, v129, vcc
	v_cmp_gt_i32_e32 vcc, s1, v94
	v_sub_u32_e32 v98, v137, v98
	v_lshlrev_b32_e32 v102, s4, v102
	v_or_b32_e32 v106, 0x68, v144
	v_cndmask_b32_e32 v95, v138, v132, vcc
	v_cndmask_b32_e32 v97, v126, v127, vcc
	v_cndmask_b32_e32 v96, v128, v129, vcc
	v_cmp_gt_i32_e32 vcc, s1, v98
	v_sub_u32_e32 v102, v137, v102
	v_lshlrev_b32_e32 v106, s4, v106
	v_or_b32_e32 v110, 0x6c, v144
	v_cndmask_b32_e32 v99, v138, v132, vcc
	v_cndmask_b32_e32 v101, v126, v127, vcc
	v_cndmask_b32_e32 v100, v128, v129, vcc
	v_cmp_gt_i32_e32 vcc, s1, v102
	v_sub_u32_e32 v106, v137, v106
	v_lshlrev_b32_e32 v110, s4, v110
	v_or_b32_e32 v114, 0x70, v144
	v_cndmask_b32_e32 v103, v138, v132, vcc
	v_cndmask_b32_e32 v105, v126, v127, vcc
	v_cndmask_b32_e32 v104, v128, v129, vcc
	v_cmp_gt_i32_e32 vcc, s1, v106
	v_sub_u32_e32 v110, v137, v110
	v_lshlrev_b32_e32 v114, s4, v114
	v_or_b32_e32 v118, 0x74, v144
	v_cndmask_b32_e32 v107, v138, v132, vcc
	v_cndmask_b32_e32 v109, v126, v127, vcc
	v_cndmask_b32_e32 v108, v128, v129, vcc
	v_cmp_gt_i32_e32 vcc, s1, v110
	v_sub_u32_e32 v114, v137, v114
	v_lshlrev_b32_e32 v118, s4, v118
	v_or_b32_e32 v122, 0x78, v144
	v_cndmask_b32_e32 v111, v138, v132, vcc
	v_cndmask_b32_e32 v113, v126, v127, vcc
	v_cndmask_b32_e32 v112, v128, v129, vcc
	v_cmp_gt_i32_e32 vcc, s1, v114
	v_sub_u32_e32 v118, v137, v118
	v_lshlrev_b32_e32 v122, s4, v122
	v_or_b32_e32 v133, 0x7c, v144
	v_cndmask_b32_e32 v115, v138, v132, vcc
	v_cndmask_b32_e32 v117, v126, v127, vcc
	v_cndmask_b32_e32 v116, v128, v129, vcc
	v_cmp_gt_i32_e32 vcc, s1, v118
	v_sub_u32_e32 v122, v137, v122
	v_lshlrev_b32_e32 v133, s4, v133
	v_cndmask_b32_e32 v119, v138, v132, vcc
	v_cndmask_b32_e32 v121, v126, v127, vcc
	v_cndmask_b32_e32 v120, v128, v129, vcc
	v_cmp_gt_i32_e32 vcc, s1, v122
	v_sub_u32_e32 v133, v137, v133
	v_add_u32_e32 v2, v3, v2
	v_cndmask_b32_e32 v123, v138, v132, vcc
	v_cndmask_b32_e32 v125, v126, v127, vcc
	v_cndmask_b32_e32 v124, v128, v129, vcc
	v_cmp_gt_i32_e32 vcc, s1, v133
	v_add_u32_e32 v6, v7, v6
	v_add_u32_e32 v10, v11, v10
	v_cndmask_b32_e32 v145, v138, v132, vcc
	v_add_u32_e32 v14, v15, v14
	v_add_u32_e32 v18, v19, v18
	v_add_u32_e32 v22, v23, v22
	v_add_u32_e32 v26, v27, v26
	v_add_u32_e32 v30, v31, v30
	v_add_u32_e32 v34, v35, v34
	v_add_u32_e32 v38, v39, v38
	v_add_u32_e32 v42, v43, v42
	v_add_u32_e32 v46, v47, v46
	v_add_u32_e32 v50, v51, v50
	v_add_u32_e32 v54, v55, v54
	v_add_u32_e32 v58, v59, v58
	v_add_u32_e32 v62, v63, v62
	v_add_u32_e32 v66, v67, v66
	v_add_u32_e32 v70, v71, v70
	v_add_u32_e32 v74, v75, v74
	v_add_u32_e32 v78, v79, v78
	v_add_u32_e32 v82, v83, v82
	v_add_u32_e32 v86, v87, v86
	v_add_u32_e32 v90, v91, v90
	v_add_u32_e32 v94, v95, v94
	v_add_u32_e32 v98, v99, v98
	v_add_u32_e32 v102, v103, v102
	v_add_u32_e32 v106, v107, v106
	v_add_u32_e32 v110, v111, v110
	v_add_u32_e32 v114, v115, v114
	v_add_u32_e32 v118, v119, v118
	v_add_u32_e32 v122, v123, v122
	v_add_u32_e32 v146, v145, v133
	v_ashrrev_i32_e32 v3, 31, v2
	v_ashrrev_i32_e32 v7, 31, v6
	v_ashrrev_i32_e32 v11, 31, v10
	v_ashrrev_i32_e32 v15, 31, v14
	v_ashrrev_i32_e32 v19, 31, v18
	v_ashrrev_i32_e32 v23, 31, v22
	v_ashrrev_i32_e32 v27, 31, v26
	v_ashrrev_i32_e32 v31, 31, v30
	v_ashrrev_i32_e32 v35, 31, v34
	v_ashrrev_i32_e32 v39, 31, v38
	v_ashrrev_i32_e32 v43, 31, v42
	v_ashrrev_i32_e32 v47, 31, v46
	v_ashrrev_i32_e32 v51, 31, v50
	v_ashrrev_i32_e32 v55, 31, v54
	v_ashrrev_i32_e32 v59, 31, v58
	v_ashrrev_i32_e32 v63, 31, v62
	v_ashrrev_i32_e32 v67, 31, v66
	v_ashrrev_i32_e32 v71, 31, v70
	v_ashrrev_i32_e32 v75, 31, v74
	v_ashrrev_i32_e32 v79, 31, v78
	v_ashrrev_i32_e32 v83, 31, v82
	v_ashrrev_i32_e32 v87, 31, v86
	v_ashrrev_i32_e32 v91, 31, v90
	v_ashrrev_i32_e32 v95, 31, v94
	v_ashrrev_i32_e32 v99, 31, v98
	v_ashrrev_i32_e32 v103, 31, v102
	v_ashrrev_i32_e32 v107, 31, v106
	v_ashrrev_i32_e32 v111, 31, v110
	v_ashrrev_i32_e32 v115, 31, v114
	v_ashrrev_i32_e32 v119, 31, v118
	v_ashrrev_i32_e32 v123, 31, v122
	v_ashrrev_i32_e32 v147, 31, v146
	v_lshlrev_b64 v[2:3], 11, v[2:3]
	v_lshlrev_b64 v[6:7], 11, v[6:7]
	v_lshlrev_b64 v[10:11], 11, v[10:11]
	v_lshlrev_b64 v[14:15], 11, v[14:15]
	v_lshlrev_b64 v[18:19], 11, v[18:19]
	v_lshlrev_b64 v[22:23], 11, v[22:23]
	v_lshlrev_b64 v[26:27], 11, v[26:27]
	v_lshlrev_b64 v[30:31], 11, v[30:31]
	v_lshlrev_b64 v[34:35], 11, v[34:35]
	v_lshlrev_b64 v[38:39], 11, v[38:39]
	v_lshlrev_b64 v[42:43], 11, v[42:43]
	v_lshlrev_b64 v[46:47], 11, v[46:47]
	v_lshlrev_b64 v[50:51], 11, v[50:51]
	v_lshlrev_b64 v[54:55], 11, v[54:55]
	v_lshlrev_b64 v[58:59], 11, v[58:59]
	v_lshlrev_b64 v[62:63], 11, v[62:63]
	v_lshlrev_b64 v[66:67], 11, v[66:67]
	v_lshlrev_b64 v[70:71], 11, v[70:71]
	v_lshlrev_b64 v[74:75], 11, v[74:75]
	v_lshlrev_b64 v[78:79], 11, v[78:79]
	v_lshlrev_b64 v[82:83], 11, v[82:83]
	v_lshlrev_b64 v[86:87], 11, v[86:87]
	v_lshlrev_b64 v[90:91], 11, v[90:91]
	v_lshlrev_b64 v[94:95], 11, v[94:95]
	v_lshlrev_b64 v[98:99], 11, v[98:99]
	v_lshlrev_b64 v[102:103], 11, v[102:103]
	v_lshlrev_b64 v[106:107], 11, v[106:107]
	v_lshlrev_b64 v[110:111], 11, v[110:111]
	v_lshlrev_b64 v[114:115], 11, v[114:115]
	v_lshlrev_b64 v[118:119], 11, v[118:119]
	v_lshlrev_b64 v[122:123], 11, v[122:123]
	v_cndmask_b32_e32 v127, v126, v127, vcc
	v_cndmask_b32_e32 v126, v128, v129, vcc
	v_lshlrev_b64 v[128:129], 11, v[146:147]
	v_lshl_add_u64 v[2:3], v[4:5], 0, v[2:3]
	v_lshl_add_u64 v[6:7], v[8:9], 0, v[6:7]
	v_lshl_add_u64 v[10:11], v[12:13], 0, v[10:11]
	v_lshl_add_u64 v[14:15], v[16:17], 0, v[14:15]
	v_lshl_add_u64 v[18:19], v[20:21], 0, v[18:19]
	v_lshl_add_u64 v[22:23], v[24:25], 0, v[22:23]
	v_lshl_add_u64 v[26:27], v[28:29], 0, v[26:27]
	v_lshl_add_u64 v[30:31], v[32:33], 0, v[30:31]
	v_lshl_add_u64 v[34:35], v[36:37], 0, v[34:35]
	v_lshl_add_u64 v[38:39], v[40:41], 0, v[38:39]
	v_lshl_add_u64 v[42:43], v[44:45], 0, v[42:43]
	v_lshl_add_u64 v[46:47], v[48:49], 0, v[46:47]
	v_lshl_add_u64 v[50:51], v[52:53], 0, v[50:51]
	v_lshl_add_u64 v[54:55], v[56:57], 0, v[54:55]
	v_lshl_add_u64 v[58:59], v[60:61], 0, v[58:59]
	v_lshl_add_u64 v[62:63], v[64:65], 0, v[62:63]
	v_lshl_add_u64 v[66:67], v[68:69], 0, v[66:67]
	v_lshl_add_u64 v[70:71], v[72:73], 0, v[70:71]
	v_lshl_add_u64 v[74:75], v[76:77], 0, v[74:75]
	v_lshl_add_u64 v[78:79], v[80:81], 0, v[78:79]
	v_lshl_add_u64 v[82:83], v[84:85], 0, v[82:83]
	v_lshl_add_u64 v[86:87], v[88:89], 0, v[86:87]
	v_lshl_add_u64 v[90:91], v[92:93], 0, v[90:91]
	v_lshl_add_u64 v[94:95], v[96:97], 0, v[94:95]
	v_lshl_add_u64 v[98:99], v[100:101], 0, v[98:99]
	v_lshl_add_u64 v[102:103], v[104:105], 0, v[102:103]
	v_lshl_add_u64 v[106:107], v[108:109], 0, v[106:107]
	v_lshl_add_u64 v[110:111], v[112:113], 0, v[110:111]
	v_lshl_add_u64 v[114:115], v[116:117], 0, v[114:115]
	v_lshl_add_u64 v[118:119], v[120:121], 0, v[118:119]
	v_lshl_add_u64 v[122:123], v[124:125], 0, v[122:123]
	v_lshl_add_u64 v[126:127], v[126:127], 0, v[128:129]
	v_lshl_add_u64 v[2:3], v[2:3], 0, v[134:135]
	v_mov_b32_e32 v131, v135
	v_lshl_add_u64 v[6:7], v[6:7], 0, v[134:135]
	v_lshl_add_u64 v[10:11], v[10:11], 0, v[134:135]
	v_lshl_add_u64 v[14:15], v[14:15], 0, v[134:135]
	v_lshl_add_u64 v[18:19], v[18:19], 0, v[134:135]
	v_lshl_add_u64 v[22:23], v[22:23], 0, v[134:135]
	v_lshl_add_u64 v[26:27], v[26:27], 0, v[134:135]
	v_lshl_add_u64 v[30:31], v[30:31], 0, v[134:135]
	v_lshl_add_u64 v[34:35], v[34:35], 0, v[134:135]
	v_lshl_add_u64 v[38:39], v[38:39], 0, v[134:135]
	v_lshl_add_u64 v[42:43], v[42:43], 0, v[134:135]
	v_lshl_add_u64 v[46:47], v[46:47], 0, v[134:135]
	v_lshl_add_u64 v[50:51], v[50:51], 0, v[134:135]
	v_lshl_add_u64 v[54:55], v[54:55], 0, v[134:135]
	v_lshl_add_u64 v[58:59], v[58:59], 0, v[134:135]
	v_lshl_add_u64 v[62:63], v[62:63], 0, v[134:135]
	v_lshl_add_u64 v[66:67], v[66:67], 0, v[134:135]
	v_lshl_add_u64 v[70:71], v[70:71], 0, v[134:135]
	v_lshl_add_u64 v[74:75], v[74:75], 0, v[134:135]
	v_lshl_add_u64 v[78:79], v[78:79], 0, v[134:135]
	v_lshl_add_u64 v[82:83], v[82:83], 0, v[134:135]
	v_lshl_add_u64 v[86:87], v[86:87], 0, v[134:135]
	v_lshl_add_u64 v[90:91], v[90:91], 0, v[134:135]
	v_lshl_add_u64 v[94:95], v[94:95], 0, v[134:135]
	v_lshl_add_u64 v[98:99], v[98:99], 0, v[134:135]
	v_lshl_add_u64 v[102:103], v[102:103], 0, v[134:135]
	v_lshl_add_u64 v[106:107], v[106:107], 0, v[134:135]
	v_lshl_add_u64 v[110:111], v[110:111], 0, v[134:135]
	v_lshl_add_u64 v[114:115], v[114:115], 0, v[134:135]
	v_lshl_add_u64 v[118:119], v[118:119], 0, v[134:135]
	v_lshl_add_u64 v[122:123], v[122:123], 0, v[134:135]
	v_lshl_add_u64 v[126:127], v[126:127], 0, v[134:135]
	v_lshl_add_u64 v[2:3], v[2:3], 0, v[130:131]
	v_lshl_add_u64 v[6:7], v[6:7], 0, v[130:131]
	v_lshl_add_u64 v[10:11], v[10:11], 0, v[130:131]
	v_lshl_add_u64 v[14:15], v[14:15], 0, v[130:131]
	v_lshl_add_u64 v[18:19], v[18:19], 0, v[130:131]
	v_lshl_add_u64 v[22:23], v[22:23], 0, v[130:131]
	v_lshl_add_u64 v[26:27], v[26:27], 0, v[130:131]
	v_lshl_add_u64 v[30:31], v[30:31], 0, v[130:131]
	v_lshl_add_u64 v[34:35], v[34:35], 0, v[130:131]
	v_lshl_add_u64 v[38:39], v[38:39], 0, v[130:131]
	v_lshl_add_u64 v[42:43], v[42:43], 0, v[130:131]
	v_lshl_add_u64 v[46:47], v[46:47], 0, v[130:131]
	v_lshl_add_u64 v[50:51], v[50:51], 0, v[130:131]
	v_lshl_add_u64 v[54:55], v[54:55], 0, v[130:131]
	v_lshl_add_u64 v[58:59], v[58:59], 0, v[130:131]
	v_lshl_add_u64 v[62:63], v[62:63], 0, v[130:131]
	v_lshl_add_u64 v[66:67], v[66:67], 0, v[130:131]
	v_lshl_add_u64 v[70:71], v[70:71], 0, v[130:131]
	v_lshl_add_u64 v[74:75], v[74:75], 0, v[130:131]
	v_lshl_add_u64 v[78:79], v[78:79], 0, v[130:131]
	v_lshl_add_u64 v[82:83], v[82:83], 0, v[130:131]
	v_lshl_add_u64 v[86:87], v[86:87], 0, v[130:131]
	v_lshl_add_u64 v[90:91], v[90:91], 0, v[130:131]
	v_lshl_add_u64 v[94:95], v[94:95], 0, v[130:131]
	v_lshl_add_u64 v[98:99], v[98:99], 0, v[130:131]
	v_lshl_add_u64 v[102:103], v[102:103], 0, v[130:131]
	v_lshl_add_u64 v[106:107], v[106:107], 0, v[130:131]
	v_lshl_add_u64 v[110:111], v[110:111], 0, v[130:131]
	v_lshl_add_u64 v[114:115], v[114:115], 0, v[130:131]
	v_lshl_add_u64 v[118:119], v[118:119], 0, v[130:131]
	v_lshl_add_u64 v[122:123], v[122:123], 0, v[130:131]
	v_lshl_add_u64 v[126:127], v[126:127], 0, v[130:131]
	v_subrev_u32_e32 v131, s1, v137
	v_cmp_gt_i32_e32 vcc, s1, v131
	s_and_b64 s[2:3], vcc, exec
	s_cselect_b32 s3, s13, s9
	v_cndmask_b32_e32 v132, v138, v132, vcc
	v_add_u32_e32 v132, v132, v131
	v_ashrrev_i32_e32 v133, 31, v132
	s_cselect_b32 s2, s12, s8
	v_lshlrev_b64 v[132:133], 11, v[132:133]
	v_lshl_add_u64 v[132:133], s[2:3], 0, v[132:133]
	v_lshl_add_u64 v[132:133], v[132:133], 0, v[134:135]
	s_waitcnt lgkmcnt(0)
	global_load_dwordx4 v[2:5], v[2:3], off offset:1024
	v_readfirstlane_b32 s2, v132
	v_readfirstlane_b32 s3, v133
	global_load_dwordx4 v[6:9], v[6:7], off offset:1024
	v_add_f32_e32 v134, v136, v143
	global_load_dwordx4 v[10:13], v[10:11], off offset:1024
	ds_bpermute_b32 v136, v139, v134
	global_load_dwordx4 v[14:17], v[14:15], off offset:1024
	v_readfirstlane_b32 s1, v172
	global_load_dwordx4 v[18:21], v[18:19], off offset:1024
	v_cmp_gt_u32_e32 vcc, 16, v178
	global_load_dwordx4 v[22:25], v[22:23], off offset:1024
	s_waitcnt lgkmcnt(0)
	v_add_f32_e32 v134, v134, v136
	global_load_dwordx4 v[26:29], v[26:27], off offset:1024
	ds_bpermute_b32 v136, v140, v134
	global_load_dwordx4 v[30:33], v[30:31], off offset:1024
	s_waitcnt lgkmcnt(0)
	v_add_f32_e32 v134, v134, v136
	global_load_dwordx4 v[34:37], v[34:35], off offset:1024
	ds_bpermute_b32 v136, v141, v134
	global_load_dwordx4 v[38:41], v[38:39], off offset:1024
	s_waitcnt lgkmcnt(0)
	v_add_f32_e32 v134, v134, v136
	global_load_dwordx4 v[42:45], v[42:43], off offset:1024
	ds_bpermute_b32 v136, v142, v134
	global_load_dwordx4 v[46:49], v[46:47], off offset:1024
	s_waitcnt lgkmcnt(0)
	v_add_f32_e32 v134, v134, v136
	global_load_dwordx4 v[50:53], v[50:51], off offset:1024
	ds_bpermute_b32 v136, v171, v134
	global_load_dwordx4 v[54:57], v[54:55], off offset:1024
	s_waitcnt lgkmcnt(0)
	v_add_f32_e32 v134, v134, v136
	global_load_dwordx4 v[58:61], v[58:59], off offset:1024
	v_lshl_add_u32 v136, v144, 2, s0
	global_load_dwordx4 v[62:65], v[62:63], off offset:1024
	v_add_u32_e32 v136, 0x2000, v136
	global_load_dwordx4 v[66:69], v[66:67], off offset:1024
	ds_bpermute_b32 v173, v168, v134
	global_load_dwordx4 v[70:73], v[70:71], off offset:1024
	s_nop 0
	global_load_dwordx4 v[74:77], v[74:75], off offset:1024
	s_nop 0
	global_load_dwordx4 v[78:81], v[78:79], off offset:1024
	s_nop 0
	global_load_dwordx4 v[82:85], v[82:83], off offset:1024
	s_nop 0
	global_load_dwordx4 v[86:89], v[86:87], off offset:1024
	s_nop 0
	global_load_dwordx4 v[90:93], v[90:91], off offset:1024
	s_nop 0
	global_load_dwordx4 v[94:97], v[94:95], off offset:1024
	s_nop 0
	global_load_dwordx4 v[98:101], v[98:99], off offset:1024
	s_nop 0
	global_load_dwordx4 v[102:105], v[102:103], off offset:1024
	s_nop 0
	global_load_dwordx4 v[106:109], v[106:107], off offset:1024
	s_nop 0
	global_load_dwordx4 v[110:113], v[110:111], off offset:1024
	s_nop 0
	global_load_dwordx4 v[114:117], v[114:115], off offset:1024
	s_nop 0
	global_load_dwordx4 v[118:121], v[118:119], off offset:1024
	s_nop 0
	global_load_dwordx4 v[122:125], v[122:123], off offset:1024
	s_nop 0
	global_load_dwordx4 v[126:129], v[126:127], off offset:1024
	s_nop 0
	global_load_dwordx4 v[130:133], v130, s[2:3] offset:1024
	ds_read2_b32 v[166:167], v136 offset1:4
	ds_read2_b32 v[164:165], v136 offset0:8 offset1:12
	ds_read2_b32 v[162:163], v136 offset0:16 offset1:20
	ds_read2_b32 v[160:161], v136 offset0:24 offset1:28
	ds_read2_b32 v[158:159], v136 offset0:32 offset1:36
	ds_read2_b32 v[156:157], v136 offset0:40 offset1:44
	ds_read2_b32 v[154:155], v136 offset0:48 offset1:52
	ds_read2_b32 v[152:153], v136 offset0:56 offset1:60
	ds_read2_b32 v[150:151], v136 offset0:64 offset1:68
	ds_read2_b32 v[148:149], v136 offset0:72 offset1:76
	ds_read2_b32 v[146:147], v136 offset0:80 offset1:84
	ds_read2_b32 v[144:145], v136 offset0:88 offset1:92
	ds_read2_b32 v[142:143], v136 offset0:96 offset1:100
	ds_read2_b32 v[140:141], v136 offset0:104 offset1:108
	ds_read2_b32 v[138:139], v136 offset0:112 offset1:116
	ds_read2_b32 v[136:137], v136 offset0:120 offset1:124
	s_and_saveexec_b64 s[2:3], vcc
	v_mov_b32_e32 v135, s0
	ds_read_b32 v135, v135 offset:8704
	s_or_b64 exec, exec, s[2:3]
	s_waitcnt vmcnt(32) lgkmcnt(14)
	v_pk_fma_f32 v[4:5], v[4:5], v[166:167], 0 op_sel_hi:[1,0,0]
	v_pk_fma_f32 v[2:3], v[2:3], v[166:167], 0 op_sel_hi:[1,0,0]
	v_mov_b32_e32 v166, v167
	s_waitcnt vmcnt(31)
	v_pk_fma_f32 v[2:3], v[6:7], v[166:167], v[2:3] op_sel_hi:[1,0,1]
	v_pk_fma_f32 v[4:5], v[8:9], v[166:167], v[4:5] op_sel_hi:[1,0,1]
	s_waitcnt vmcnt(30)
	v_pk_fma_f32 v[2:3], v[10:11], v[164:165], v[2:3] op_sel_hi:[1,0,1]
	v_pk_fma_f32 v[4:5], v[12:13], v[164:165], v[4:5] op_sel_hi:[1,0,1]
	v_mov_b32_e32 v6, v165
	s_waitcnt vmcnt(29)
	v_pk_fma_f32 v[2:3], v[14:15], v[6:7], v[2:3] op_sel_hi:[1,0,1]
	v_pk_fma_f32 v[4:5], v[16:17], v[6:7], v[4:5] op_sel_hi:[1,0,1]
	s_waitcnt vmcnt(28) lgkmcnt(13)
	v_pk_fma_f32 v[2:3], v[18:19], v[162:163], v[2:3] op_sel_hi:[1,0,1]
	v_pk_fma_f32 v[4:5], v[20:21], v[162:163], v[4:5] op_sel_hi:[1,0,1]
	v_mov_b32_e32 v6, v163
	s_waitcnt vmcnt(27)
	v_pk_fma_f32 v[2:3], v[22:23], v[6:7], v[2:3] op_sel_hi:[1,0,1]
	v_pk_fma_f32 v[4:5], v[24:25], v[6:7], v[4:5] op_sel_hi:[1,0,1]
	s_waitcnt vmcnt(26) lgkmcnt(12)
	v_pk_fma_f32 v[2:3], v[26:27], v[160:161], v[2:3] op_sel_hi:[1,0,1]
	v_pk_fma_f32 v[4:5], v[28:29], v[160:161], v[4:5] op_sel_hi:[1,0,1]
	v_mov_b32_e32 v6, v161
	s_waitcnt vmcnt(25)
	v_pk_fma_f32 v[2:3], v[30:31], v[6:7], v[2:3] op_sel_hi:[1,0,1]
	v_pk_fma_f32 v[4:5], v[32:33], v[6:7], v[4:5] op_sel_hi:[1,0,1]
	s_waitcnt vmcnt(24) lgkmcnt(11)
	v_pk_fma_f32 v[2:3], v[34:35], v[158:159], v[2:3] op_sel_hi:[1,0,1]
	v_pk_fma_f32 v[4:5], v[36:37], v[158:159], v[4:5] op_sel_hi:[1,0,1]
	v_mov_b32_e32 v6, v159
	s_waitcnt vmcnt(23)
	v_pk_fma_f32 v[2:3], v[38:39], v[6:7], v[2:3] op_sel_hi:[1,0,1]
	v_pk_fma_f32 v[4:5], v[40:41], v[6:7], v[4:5] op_sel_hi:[1,0,1]
	s_waitcnt vmcnt(22) lgkmcnt(10)
	v_pk_fma_f32 v[2:3], v[42:43], v[156:157], v[2:3] op_sel_hi:[1,0,1]
	v_pk_fma_f32 v[4:5], v[44:45], v[156:157], v[4:5] op_sel_hi:[1,0,1]
	v_mov_b32_e32 v6, v157
	s_waitcnt vmcnt(21)
	v_pk_fma_f32 v[2:3], v[46:47], v[6:7], v[2:3] op_sel_hi:[1,0,1]
	v_pk_fma_f32 v[4:5], v[48:49], v[6:7], v[4:5] op_sel_hi:[1,0,1]
	s_waitcnt vmcnt(20) lgkmcnt(9)
	v_pk_fma_f32 v[2:3], v[50:51], v[154:155], v[2:3] op_sel_hi:[1,0,1]
	v_pk_fma_f32 v[4:5], v[52:53], v[154:155], v[4:5] op_sel_hi:[1,0,1]
	v_mov_b32_e32 v6, v155
	s_waitcnt vmcnt(19)
	v_pk_fma_f32 v[2:3], v[54:55], v[6:7], v[2:3] op_sel_hi:[1,0,1]
	v_pk_fma_f32 v[4:5], v[56:57], v[6:7], v[4:5] op_sel_hi:[1,0,1]
	s_waitcnt vmcnt(18) lgkmcnt(8)
	v_pk_fma_f32 v[2:3], v[58:59], v[152:153], v[2:3] op_sel_hi:[1,0,1]
	v_pk_fma_f32 v[4:5], v[60:61], v[152:153], v[4:5] op_sel_hi:[1,0,1]
	v_mov_b32_e32 v6, v153
	s_waitcnt vmcnt(17)
	v_pk_fma_f32 v[2:3], v[62:63], v[6:7], v[2:3] op_sel_hi:[1,0,1]
	v_pk_fma_f32 v[4:5], v[64:65], v[6:7], v[4:5] op_sel_hi:[1,0,1]
	s_waitcnt vmcnt(16) lgkmcnt(7)
	v_pk_fma_f32 v[2:3], v[66:67], v[150:151], v[2:3] op_sel_hi:[1,0,1]
	v_pk_fma_f32 v[4:5], v[68:69], v[150:151], v[4:5] op_sel_hi:[1,0,1]
	v_mov_b32_e32 v6, v151
	s_waitcnt vmcnt(15)
	v_pk_fma_f32 v[2:3], v[70:71], v[6:7], v[2:3] op_sel_hi:[1,0,1]
	v_pk_fma_f32 v[4:5], v[72:73], v[6:7], v[4:5] op_sel_hi:[1,0,1]
	s_waitcnt vmcnt(14) lgkmcnt(6)
	v_pk_fma_f32 v[2:3], v[74:75], v[148:149], v[2:3] op_sel_hi:[1,0,1]
	v_pk_fma_f32 v[4:5], v[76:77], v[148:149], v[4:5] op_sel_hi:[1,0,1]
	v_mov_b32_e32 v6, v149
	s_waitcnt vmcnt(13)
	v_pk_fma_f32 v[2:3], v[78:79], v[6:7], v[2:3] op_sel_hi:[1,0,1]
	v_pk_fma_f32 v[4:5], v[80:81], v[6:7], v[4:5] op_sel_hi:[1,0,1]
	s_waitcnt vmcnt(12) lgkmcnt(5)
	v_pk_fma_f32 v[2:3], v[82:83], v[146:147], v[2:3] op_sel_hi:[1,0,1]
	v_pk_fma_f32 v[4:5], v[84:85], v[146:147], v[4:5] op_sel_hi:[1,0,1]
	v_mov_b32_e32 v6, v147
	s_waitcnt vmcnt(11)
	v_pk_fma_f32 v[2:3], v[86:87], v[6:7], v[2:3] op_sel_hi:[1,0,1]
	v_pk_fma_f32 v[4:5], v[88:89], v[6:7], v[4:5] op_sel_hi:[1,0,1]
	s_waitcnt vmcnt(10) lgkmcnt(4)
	v_pk_fma_f32 v[2:3], v[90:91], v[144:145], v[2:3] op_sel_hi:[1,0,1]
	v_pk_fma_f32 v[4:5], v[92:93], v[144:145], v[4:5] op_sel_hi:[1,0,1]
	v_mov_b32_e32 v6, v145
	s_waitcnt vmcnt(9)
	v_pk_fma_f32 v[2:3], v[94:95], v[6:7], v[2:3] op_sel_hi:[1,0,1]
	v_pk_fma_f32 v[4:5], v[96:97], v[6:7], v[4:5] op_sel_hi:[1,0,1]
	s_waitcnt vmcnt(8) lgkmcnt(3)
	v_pk_fma_f32 v[2:3], v[98:99], v[142:143], v[2:3] op_sel_hi:[1,0,1]
	v_pk_fma_f32 v[4:5], v[100:101], v[142:143], v[4:5] op_sel_hi:[1,0,1]
	v_mov_b32_e32 v6, v143
	s_waitcnt vmcnt(7)
	v_pk_fma_f32 v[2:3], v[102:103], v[6:7], v[2:3] op_sel_hi:[1,0,1]
	v_pk_fma_f32 v[4:5], v[104:105], v[6:7], v[4:5] op_sel_hi:[1,0,1]
	s_waitcnt vmcnt(6) lgkmcnt(2)
	v_pk_fma_f32 v[2:3], v[106:107], v[140:141], v[2:3] op_sel_hi:[1,0,1]
	v_pk_fma_f32 v[4:5], v[108:109], v[140:141], v[4:5] op_sel_hi:[1,0,1]
	v_mov_b32_e32 v6, v141
	s_waitcnt vmcnt(5)
	v_pk_fma_f32 v[2:3], v[110:111], v[6:7], v[2:3] op_sel_hi:[1,0,1]
	v_pk_fma_f32 v[4:5], v[112:113], v[6:7], v[4:5] op_sel_hi:[1,0,1]
	s_waitcnt vmcnt(4) lgkmcnt(1)
	v_pk_fma_f32 v[2:3], v[114:115], v[138:139], v[2:3] op_sel_hi:[1,0,1]
	v_pk_fma_f32 v[4:5], v[116:117], v[138:139], v[4:5] op_sel_hi:[1,0,1]
	v_mov_b32_e32 v6, v139
	s_waitcnt vmcnt(3)
	v_pk_fma_f32 v[2:3], v[118:119], v[6:7], v[2:3] op_sel_hi:[1,0,1]
	v_pk_fma_f32 v[4:5], v[120:121], v[6:7], v[4:5] op_sel_hi:[1,0,1]
	s_waitcnt vmcnt(2) lgkmcnt(0)
	v_pk_fma_f32 v[2:3], v[122:123], v[136:137], v[2:3] op_sel_hi:[1,0,1]
	v_pk_fma_f32 v[4:5], v[124:125], v[136:137], v[4:5] op_sel_hi:[1,0,1]
	v_mov_b32_e32 v6, v137
	s_waitcnt vmcnt(1)
	v_pk_fma_f32 v[2:3], v[126:127], v[6:7], v[2:3] op_sel_hi:[1,0,1]
	v_pk_fma_f32 v[4:5], v[128:129], v[6:7], v[4:5] op_sel_hi:[1,0,1]
	v_mov_b32_e32 v6, v135
	s_waitcnt vmcnt(0)
	v_pk_fma_f32 v[2:3], v[130:131], v[6:7], v[2:3] op_sel_hi:[1,0,1]
	v_pk_fma_f32 v[6:7], v[132:133], v[6:7], v[4:5] op_sel_hi:[1,0,1]
	ds_bpermute_b32 v8, v171, v2
	ds_bpermute_b32 v9, v171, v3
	ds_bpermute_b32 v10, v171, v6
	ds_bpermute_b32 v11, v171, v7
	s_mul_i32 s2, s79, 0xfffffd40
	s_add_i32 s0, s0, s2
	s_waitcnt lgkmcnt(2)
	v_pk_add_f32 v[2:3], v[2:3], v[8:9]
	ds_bpermute_b32 v4, v168, v2
	s_waitcnt lgkmcnt(1)
	v_pk_add_f32 v[6:7], v[6:7], v[10:11]
	ds_bpermute_b32 v5, v168, v3
	ds_bpermute_b32 v8, v168, v6
	ds_bpermute_b32 v9, v168, v7
	v_add_f32_e32 v10, v134, v173
	v_add_f32_e32 v10, s1, v10
	s_and_saveexec_b64 s[8:9], vcc
	s_cbranch_execz .LBB0_727
	v_div_scale_f32 v11, s[2:3], v10, v10, 1.0
	v_rcp_f32_e32 v12, v11
	v_lshlrev_b32_e32 v13, 2, v169
	s_waitcnt lgkmcnt(2)
	v_pk_add_f32 v[2:3], v[2:3], v[4:5]
	s_waitcnt lgkmcnt(0)
	v_pk_add_f32 v[4:5], v[6:7], v[8:9]
	v_fma_f32 v14, -v11, v12, 1.0
	v_fmac_f32_e32 v12, v14, v12
	v_div_scale_f32 v14, vcc, 1.0, v10, 1.0
	v_mul_f32_e32 v15, v14, v12
	v_fma_f32 v16, -v11, v15, v14
	v_fmac_f32_e32 v15, v16, v12
	v_fma_f32 v11, -v11, v15, v14
	v_div_fmas_f32 v11, v11, v12, v15
	v_div_fixup_f32 v12, v11, v10, 1.0
	v_lshl_add_u32 v11, v13, 2, s0
	v_pk_mul_f32 v[2:3], v[12:13], v[2:3] op_sel_hi:[0,1]
	v_pk_mul_f32 v[4:5], v[12:13], v[4:5] op_sel_hi:[0,1]
	ds_write_b128 v11, v[2:5] offset:16384
